# speedup vs baseline: 1.0015x; 1.0015x over previous
; __device__ __forceinline__ unsigned pk2(float lo, float hi) { f32x2 v = {lo, hi}; bf16x2_t b = __builtin_convertvector(v, bf16x2_t); return __builtin_bit_cast(unsigned, b); }
; __device__ __forceinline__ float silu_f(float z) { return z * __builtin_amdgcn_rcpf(1.0f + __expf(-z)); }
; __device__ __forceinline__ int launder_v(int x) { asm volatile("" : "+v"(x)); return x; }
; __device__ __forceinline__ int launder_s(int x) { asm volatile("" : "+s"(x)); return x; }
; __device__ __forceinline__ float swap_add(float v) { unsigned a = __builtin_bit_cast(unsigned, v), b = a; asm volatile("s_nop 1\n\tv_permlane32_swap_b32 %0, %1\n\ts_nop 1" : "+v"(a), "+v"(b)); return __builtin_bit_cast(float, a) + __builtin_bit_cast(float, b); }
; template <int MODE>
; __device__ __forceinline__ void attn_unit(LAS unsigned char* lds, const bf16_t* __restrict__ qkvz, bf16_t* __restrict__ A2, const int b, const int hd, const int qb, const AttnX& X, const int tid) {
;     ...
;     const float l_tot = swap_add(l_run);
;     const float inv = 1.0f / l_tot;
;     const int lane_e = launder_v(lane);
;     const size_t trow = (size_t)launder_s(b) * SEQ + launder_s(q0w) + (lane_e & 31);
;     if (MODE != 0) {
;         const int hh_e = lane_e >> 5;
;         u32x2 zz[NDT * 4];
; #pragma unroll
;         for (int d = 0; d < NDT; ++d)
; #pragma unroll
;             for (int i4 = 0; i4 < 4; ++i4) zz[d * 4 + i4] = *(const u32x2*)(qkvz + trow * LD + zcol + 32 * d + 8 * i4 + 4 * hh_e);
; #pragma unroll
;         for (int d = 0; d < NDT; ++d)
; #pragma unroll
;             for (int i4 = 0; i4 < 4; ++i4) { const int dd = 32 * d + 8 * i4 + 4 * hh_e; const u32x2 z2 = zz[d * 4 + i4];
;                 u32x2 w;
;                 w.x = pk2(O[d][4 * i4 + 0] * inv * silu_f(bflo(z2.x)), O[d][4 * i4 + 1] * inv * silu_f(bfhi(z2.x)));
;                 w.y = pk2(O[d][4 * i4 + 2] * inv * silu_f(bflo(z2.y)), O[d][4 * i4 + 3] * inv * silu_f(bfhi(z2.y)));
;                 *(u32x2*)(A2 + trow * DM + hd * C::DV + dd) = w; }
.Lband_pf_skip:
	s_or_b64 exec, exec, s[46:47]
	s_nop 1
	v_mov_b32_e32 v40, v146
	v_mov_b32_e32 v36, v125
	s_nop 1
	v_permlane32_swap_b32 v146, v40
	s_nop 1
	s_ashr_i32 s29, s28, 31
	s_lshl_b64 s[0:1], s[28:29], 13
	s_ashr_i32 s12, s39, 31
	s_add_u32 s0, s0, s39
	v_and_b32_e32 v80, 31, v36
	s_addc_u32 s1, s1, s12
	v_lshl_add_u64 v[32:33], s[0:1], 0, v[80:81]
	v_ashrrev_i32_e32 v36, 3, v36
	v_lshlrev_b64 v[34:35], 14, v[32:33]
	v_and_b32_e32 v36, -4, v36
	v_lshl_add_u64 v[34:35], s[84:85], 0, v[34:35]
	v_ashrrev_i32_e32 v37, 31, v36
	v_lshl_add_u64 v[34:35], v[34:35], 0, s[14:15]
	v_lshlrev_b64 v[36:37], 1, v[36:37]
	v_lshl_add_u64 v[34:35], v[34:35], 0, v[36:37]
	v_add_co_u32_e32 v38, vcc, s33, v34
	v_add_f32_e32 v52, v146, v40
	s_nop 0
	v_addc_co_u32_e32 v39, vcc, 0, v35, vcc
	global_load_dwordx2 v[42:43], v[38:39], off
	v_lshl_add_u64 v[34:35], v[34:35], 0, s[26:27]
	global_load_dwordx2 v[44:45], v[34:35], off offset:16
	global_load_dwordx2 v[46:47], v[34:35], off offset:32
	v_div_scale_f32 v53, s[0:1], v52, v52, 1.0
	v_rcp_f32_e32 v54, v53
	v_lshlrev_b64 v[32:33], 12, v[32:33]
	v_lshl_add_u64 v[32:33], s[94:95], 0, v[32:33]
	v_lshl_add_u64 v[32:33], v[32:33], 0, s[14:15]
	v_fma_f32 v38, -v53, v54, 1.0
	v_fmac_f32_e32 v54, v38, v54
	v_lshl_add_u64 v[32:33], v[32:33], 0, v[36:37]
	global_load_dwordx2 v[48:49], v[34:35], off offset:48
	global_load_dwordx2 v[50:51], v[34:35], off offset:64
	global_load_dwordx2 v[40:41], v[34:35], off offset:80
	global_load_dwordx2 v[38:39], v[34:35], off offset:96
	global_load_dwordx2 v[36:37], v[34:35], off offset:112
	v_div_scale_f32 v55, vcc, 1.0, v52, 1.0
	v_mul_f32_e32 v56, v55, v54
	v_fma_f32 v57, -v53, v56, v55
	v_fmac_f32_e32 v56, v57, v54
	v_fma_f32 v34, -v53, v56, v55
	v_div_fmas_f32 v34, v34, v54, v56
	v_div_fixup_f32 v34, v34, v52, 1.0
	v_pk_mul_f32 v[16:17], v[16:17], v[34:35] op_sel_hi:[1,0]
	v_pk_mul_f32 v[18:19], v[18:19], v[34:35] op_sel_hi:[1,0]
	v_pk_mul_f32 v[20:21], v[20:21], v[34:35] op_sel_hi:[1,0]
	v_pk_mul_f32 v[22:23], v[22:23], v[34:35] op_sel_hi:[1,0]
	s_waitcnt vmcnt(7)
	v_lshlrev_b32_e32 v52, 16, v42
	v_and_b32_e32 v53, 0xffff0000, v42
	v_lshlrev_b32_e32 v42, 16, v43
	v_and_b32_e32 v43, 0xffff0000, v43
	s_waitcnt vmcnt(6)
	v_lshlrev_b32_e32 v54, 16, v44
	v_mul_f32_e32 v35, 0xbfb8aa3b, v52
	v_mul_f32_e32 v56, 0xbfb8aa3b, v53
	v_mul_f32_e32 v57, 0xbfb8aa3b, v42
	v_mul_f32_e32 v58, 0xbfb8aa3b, v43
	v_mul_f32_e32 v59, 0xbfb8aa3b, v54
	v_exp_f32_e32 v35, v35
	v_exp_f32_e32 v56, v56
	v_exp_f32_e32 v57, v57
	v_exp_f32_e32 v58, v58
	v_and_b32_e32 v55, 0xffff0000, v44
	v_lshlrev_b32_e32 v44, 16, v45
	v_and_b32_e32 v45, 0xffff0000, v45
	v_exp_f32_e32 v59, v59
	v_mul_f32_e32 v61, 0xbfb8aa3b, v44
	v_mul_f32_e32 v62, 0xbfb8aa3b, v45
	v_mul_f32_e32 v60, 0xbfb8aa3b, v55
	v_exp_f32_e32 v61, v61
	v_exp_f32_e32 v62, v62
	v_exp_f32_e32 v60, v60
	v_add_f32_e32 v35, 1.0, v35
	v_add_f32_e32 v63, 1.0, v56
	v_add_f32_e32 v64, 1.0, v57
	v_add_f32_e32 v65, 1.0, v58
	v_add_f32_e32 v66, 1.0, v59
	v_rcp_f32_e32 v56, v35
	v_rcp_f32_e32 v57, v63
	v_rcp_f32_e32 v58, v64
	v_rcp_f32_e32 v59, v65
	v_add_f32_e32 v68, 1.0, v61
	v_add_f32_e32 v69, 1.0, v62
	v_add_f32_e32 v67, 1.0, v60
	v_rcp_f32_e32 v62, v68
	v_rcp_f32_e32 v63, v69
	v_rcp_f32_e32 v60, v66
	v_rcp_f32_e32 v61, v67
	v_pk_mul_f32 v[52:53], v[56:57], v[52:53]
	v_pk_mul_f32 v[42:43], v[58:59], v[42:43]
	v_pk_mul_f32 v[16:17], v[16:17], v[52:53]
	v_pk_mul_f32 v[18:19], v[18:19], v[42:43]
	v_cvt_pk_bf16_f32 v16, v16, v17
	v_cvt_pk_bf16_f32 v17, v18, v19
	global_store_dwordx2 v[32:33], v[16:17], off
	v_pk_mul_f32 v[16:17], v[62:63], v[44:45]
	v_pk_mul_f32 v[54:55], v[60:61], v[54:55]
	v_pk_mul_f32 v[16:17], v[22:23], v[16:17]
	v_pk_mul_f32 v[20:21], v[20:21], v[54:55]
	v_cvt_pk_bf16_f32 v19, v16, v17
	s_waitcnt vmcnt(6)
	v_lshlrev_b32_e32 v16, 16, v46
	v_cvt_pk_bf16_f32 v18, v20, v21
	v_mul_f32_e32 v17, 0xbfb8aa3b, v16
	global_store_dwordx2 v[32:33], v[18:19], off offset:16
	v_exp_f32_e32 v18, v17
	v_and_b32_e32 v17, 0xffff0000, v46
	v_mul_f32_e32 v19, 0xbfb8aa3b, v17
	v_exp_f32_e32 v19, v19
	v_lshlrev_b32_e32 v22, 16, v47
	v_and_b32_e32 v23, 0xffff0000, v47
	v_add_f32_e32 v18, 1.0, v18
	v_pk_mul_f32 v[20:21], v[24:25], v[34:35] op_sel_hi:[1,0]
	v_add_f32_e32 v19, 1.0, v19
	v_mul_f32_e32 v24, 0xbfb8aa3b, v22
	v_mul_f32_e32 v25, 0xbfb8aa3b, v23
	v_rcp_f32_e32 v18, v18
	v_rcp_f32_e32 v19, v19
	v_exp_f32_e32 v24, v24
	v_exp_f32_e32 v25, v25
	v_pk_mul_f32 v[0:1], v[0:1], v[34:35] op_sel_hi:[1,0]
	v_pk_mul_f32 v[16:17], v[18:19], v[16:17]
	v_add_f32_e32 v18, 1.0, v24
	v_add_f32_e32 v19, 1.0, v25
	v_rcp_f32_e32 v18, v18
	v_rcp_f32_e32 v19, v19
	v_pk_mul_f32 v[16:17], v[20:21], v[16:17]
	v_pk_mul_f32 v[20:21], v[26:27], v[34:35] op_sel_hi:[1,0]
	v_cvt_pk_bf16_f32 v16, v16, v17
	v_pk_mul_f32 v[18:19], v[18:19], v[22:23]
	s_waitcnt vmcnt(6)
; __device__ __forceinline__ unsigned pk2(float lo, float hi) { f32x2 v = {lo, hi}; bf16x2_t b = __builtin_convertvector(v, bf16x2_t); return __builtin_bit_cast(unsigned, b); }
; __device__ __forceinline__ float silu_f(float z) { return z * __builtin_amdgcn_rcpf(1.0f + __expf(-z)); }
; template <int MODE>
; __device__ __forceinline__ void attn_unit(LAS unsigned char* lds, const bf16_t* __restrict__ qkvz, bf16_t* __restrict__ A2, const int b, const int hd, const int qb, const AttnX& X, const int tid) {
;     ...
;             for (int i4 = 0; i4 < 4; ++i4) { const int dd = 32 * d + 8 * i4 + 4 * hh_e; const u32x2 z2 = zz[d * 4 + i4];
;                 u32x2 w;
;                 w.x = pk2(O[d][4 * i4 + 0] * inv * silu_f(bflo(z2.x)), O[d][4 * i4 + 1] * inv * silu_f(bfhi(z2.x)));
;                 w.y = pk2(O[d][4 * i4 + 2] * inv * silu_f(bflo(z2.y)), O[d][4 * i4 + 3] * inv * silu_f(bfhi(z2.y)));
;                 *(u32x2*)(A2 + trow * DM + hd * C::DV + dd) = w; }
; __device__ __forceinline__ void phase_attn_band(const Params& p, LAS unsigned char* lds) {
;     ...
;     for (int u = bx; u < 4096; u += G) attn_unit<1>(lds, QKVZ, A2, u >> 10, (u >> 5) & 31, u & 31, X, tid);
	v_lshlrev_b32_e32 v22, 16, v49
	v_pk_mul_f32 v[18:19], v[20:21], v[18:19]
	v_and_b32_e32 v23, 0xffff0000, v49
	v_cvt_pk_bf16_f32 v17, v18, v19
	global_store_dwordx2 v[32:33], v[16:17], off offset:32
	v_lshlrev_b32_e32 v16, 16, v48
	v_mul_f32_e32 v17, 0xbfb8aa3b, v16
	v_exp_f32_e32 v18, v17
	v_and_b32_e32 v17, 0xffff0000, v48
	v_mul_f32_e32 v19, 0xbfb8aa3b, v17
	v_exp_f32_e32 v19, v19
	v_add_f32_e32 v18, 1.0, v18
	v_mul_f32_e32 v24, 0xbfb8aa3b, v22
	v_mul_f32_e32 v25, 0xbfb8aa3b, v23
	v_add_f32_e32 v19, 1.0, v19
	v_rcp_f32_e32 v18, v18
	v_rcp_f32_e32 v19, v19
	v_exp_f32_e32 v24, v24
	v_exp_f32_e32 v25, v25
	v_pk_mul_f32 v[20:21], v[28:29], v[34:35] op_sel_hi:[1,0]
	v_pk_mul_f32 v[16:17], v[18:19], v[16:17]
	v_add_f32_e32 v18, 1.0, v24
	v_add_f32_e32 v19, 1.0, v25
	v_rcp_f32_e32 v18, v18
	v_rcp_f32_e32 v19, v19
	v_pk_mul_f32 v[16:17], v[20:21], v[16:17]
	v_pk_mul_f32 v[20:21], v[30:31], v[34:35] op_sel_hi:[1,0]
	v_cvt_pk_bf16_f32 v16, v16, v17
	v_pk_mul_f32 v[18:19], v[18:19], v[22:23]
	v_pk_mul_f32 v[2:3], v[2:3], v[34:35] op_sel_hi:[1,0]
	v_pk_mul_f32 v[18:19], v[20:21], v[18:19]
	s_waitcnt vmcnt(6)
	v_lshlrev_b32_e32 v20, 16, v51
	v_cvt_pk_bf16_f32 v17, v18, v19
	global_store_dwordx2 v[32:33], v[16:17], off offset:48
	v_lshlrev_b32_e32 v16, 16, v50
	v_mul_f32_e32 v17, 0xbfb8aa3b, v16
	v_exp_f32_e32 v18, v17
	v_and_b32_e32 v17, 0xffff0000, v50
	v_mul_f32_e32 v19, 0xbfb8aa3b, v17
	v_exp_f32_e32 v19, v19
	v_and_b32_e32 v21, 0xffff0000, v51
	v_add_f32_e32 v18, 1.0, v18
	v_mul_f32_e32 v22, 0xbfb8aa3b, v20
	v_add_f32_e32 v19, 1.0, v19
	v_mul_f32_e32 v23, 0xbfb8aa3b, v21
	v_rcp_f32_e32 v18, v18
	v_rcp_f32_e32 v19, v19
	v_exp_f32_e32 v22, v22
	v_exp_f32_e32 v23, v23
	v_pk_mul_f32 v[4:5], v[4:5], v[34:35] op_sel_hi:[1,0]
	v_pk_mul_f32 v[16:17], v[18:19], v[16:17]
	v_add_f32_e32 v18, 1.0, v22
	v_add_f32_e32 v19, 1.0, v23
	v_rcp_f32_e32 v18, v18
	v_rcp_f32_e32 v19, v19
	v_pk_mul_f32 v[0:1], v[0:1], v[16:17]
	v_pk_mul_f32 v[16:17], v[18:19], v[20:21]
	s_nop 0
	v_pk_mul_f32 v[2:3], v[2:3], v[16:17]
	v_cvt_pk_bf16_f32 v0, v0, v1
	v_cvt_pk_bf16_f32 v1, v2, v3
	global_store_dwordx2 v[32:33], v[0:1], off offset:64
	s_waitcnt vmcnt(7)
	v_lshlrev_b32_e32 v0, 16, v40
	v_mul_f32_e32 v1, 0xbfb8aa3b, v0
	v_exp_f32_e32 v2, v1
	v_and_b32_e32 v1, 0xffff0000, v40
	v_mul_f32_e32 v3, 0xbfb8aa3b, v1
	v_exp_f32_e32 v3, v3
	v_lshlrev_b32_e32 v16, 16, v41
	v_and_b32_e32 v17, 0xffff0000, v41
	v_add_f32_e32 v2, 1.0, v2
	v_add_f32_e32 v3, 1.0, v3
	v_mul_f32_e32 v18, 0xbfb8aa3b, v16
	v_mul_f32_e32 v19, 0xbfb8aa3b, v17
	v_rcp_f32_e32 v2, v2
	v_rcp_f32_e32 v3, v3
	v_exp_f32_e32 v18, v18
	v_exp_f32_e32 v19, v19
	v_pk_mul_f32 v[0:1], v[2:3], v[0:1]
	v_add_f32_e32 v2, 1.0, v18
	v_add_f32_e32 v3, 1.0, v19
	v_rcp_f32_e32 v2, v2
	v_rcp_f32_e32 v3, v3
	v_pk_mul_f32 v[0:1], v[4:5], v[0:1]
	v_pk_mul_f32 v[4:5], v[6:7], v[34:35] op_sel_hi:[1,0]
	v_cvt_pk_bf16_f32 v0, v0, v1
	v_pk_mul_f32 v[2:3], v[2:3], v[16:17]
	s_waitcnt vmcnt(6)
	v_lshlrev_b32_e32 v6, 16, v39
	v_pk_mul_f32 v[2:3], v[4:5], v[2:3]
	v_and_b32_e32 v7, 0xffff0000, v39
	v_cvt_pk_bf16_f32 v1, v2, v3
	global_store_dwordx2 v[32:33], v[0:1], off offset:80
	v_lshlrev_b32_e32 v0, 16, v38
	v_mul_f32_e32 v1, 0xbfb8aa3b, v0
	v_exp_f32_e32 v2, v1
	v_and_b32_e32 v1, 0xffff0000, v38
	v_mul_f32_e32 v3, 0xbfb8aa3b, v1
	v_exp_f32_e32 v3, v3
	v_add_f32_e32 v2, 1.0, v2
	v_pk_mul_f32 v[4:5], v[8:9], v[34:35] op_sel_hi:[1,0]
	v_mul_f32_e32 v8, 0xbfb8aa3b, v6
	v_add_f32_e32 v3, 1.0, v3
	v_mul_f32_e32 v9, 0xbfb8aa3b, v7
	v_rcp_f32_e32 v2, v2
	v_rcp_f32_e32 v3, v3
	v_exp_f32_e32 v8, v8
	v_exp_f32_e32 v9, v9
	v_pk_mul_f32 v[0:1], v[2:3], v[0:1]
	v_add_f32_e32 v2, 1.0, v8
	v_add_f32_e32 v3, 1.0, v9
	v_rcp_f32_e32 v2, v2
	v_rcp_f32_e32 v3, v3
	v_pk_mul_f32 v[0:1], v[4:5], v[0:1]
	v_pk_mul_f32 v[4:5], v[10:11], v[34:35] op_sel_hi:[1,0]
	v_cvt_pk_bf16_f32 v0, v0, v1
	v_pk_mul_f32 v[2:3], v[2:3], v[6:7]
	s_waitcnt vmcnt(6)
	v_lshlrev_b32_e32 v6, 16, v37
	v_pk_mul_f32 v[2:3], v[4:5], v[2:3]
	v_and_b32_e32 v7, 0xffff0000, v37
	v_cvt_pk_bf16_f32 v1, v2, v3
	global_store_dwordx2 v[32:33], v[0:1], off offset:96
	v_lshlrev_b32_e32 v0, 16, v36
	v_mul_f32_e32 v1, 0xbfb8aa3b, v0
	v_exp_f32_e32 v2, v1
	v_and_b32_e32 v1, 0xffff0000, v36
	v_mul_f32_e32 v3, 0xbfb8aa3b, v1
	v_exp_f32_e32 v3, v3
	v_add_f32_e32 v2, 1.0, v2
	v_mul_f32_e32 v8, 0xbfb8aa3b, v6
	v_mul_f32_e32 v9, 0xbfb8aa3b, v7
	v_add_f32_e32 v3, 1.0, v3
	v_rcp_f32_e32 v2, v2
	v_rcp_f32_e32 v3, v3
	v_exp_f32_e32 v8, v8
	v_exp_f32_e32 v9, v9
	v_pk_mul_f32 v[4:5], v[12:13], v[34:35] op_sel_hi:[1,0]
	v_pk_mul_f32 v[0:1], v[2:3], v[0:1]
	v_add_f32_e32 v2, 1.0, v8
	v_add_f32_e32 v3, 1.0, v9
	v_rcp_f32_e32 v2, v2
	v_rcp_f32_e32 v3, v3
	v_pk_mul_f32 v[0:1], v[4:5], v[0:1]
	v_pk_mul_f32 v[4:5], v[14:15], v[34:35] op_sel_hi:[1,0]
	v_cvt_pk_bf16_f32 v0, v0, v1
	v_pk_mul_f32 v[2:3], v[2:3], v[6:7]
	s_nop 0
	v_pk_mul_f32 v[2:3], v[4:5], v[2:3]
	s_nop 0
	v_cvt_pk_bf16_f32 v1, v2, v3
	global_store_dwordx2 v[32:33], v[0:1], off offset:112
	v_cmp_eq_u32_e64 s[44:45], 0, v212
	s_and_saveexec_b64 s[46:47], s[44:45]
	s_cbranch_execz .Lband_nofetch
	s_waitcnt vmcnt(8)
	v_mov_b32_e32 v155, 0x23ff8
	ds_write_b32 v155, v154
.Lband_nofetch:
	s_or_b64 exec, exec, s[46:47]
	s_waitcnt lgkmcnt(0)
	s_barrier
	v_mov_b32_e32 v1, 0x23ff8
	ds_read_b32 v0, v1
	s_waitcnt lgkmcnt(0)
	v_readfirstlane_b32 s38, v0
	s_nop 1
	s_add_i32 s38, s38, s17
	s_mov_b32 s25, s38
	s_cmpk_lt_i32 s38, 0x1000
	s_cbranch_scc0 .LBB0_621

; __device__ __forceinline__ int launder_v(int x) { asm volatile("" : "+v"(x)); return x; }
; __device__ __forceinline__ int launder_s(int x) { asm volatile("" : "+s"(x)); return x; }
; __device__ __forceinline__ float swap_add(float v) { unsigned a = __builtin_bit_cast(unsigned, v), b = a; asm volatile("s_nop 1\n\tv_permlane32_swap_b32 %0, %1\n\ts_nop 1" : "+v"(a), "+v"(b)); return __builtin_bit_cast(float, a) + __builtin_bit_cast(float, b); }
; template <int MODE>
; __device__ __forceinline__ void attn_unit(LAS unsigned char* lds, const bf16_t* __restrict__ qkvz, bf16_t* __restrict__ A2, const int b, const int hd, const int qb, const AttnX& X, const int tid) {
;     ...
;     const float l_tot = swap_add(l_run);
;     const float inv = 1.0f / l_tot;
;     const int lane_e = launder_v(lane);
;     const size_t trow = (size_t)launder_s(b) * SEQ + launder_s(q0w) + (lane_e & 31);
;     if (MODE != 0) {
;         const int hh_e = lane_e >> 5;
;         u32x2 zz[NDT * 4];
; #pragma unroll
;         for (int d = 0; d < NDT; ++d)
; #pragma unroll
;             for (int i4 = 0; i4 < 4; ++i4) zz[d * 4 + i4] = *(const u32x2*)(qkvz + trow * LD + zcol + 32 * d + 8 * i4 + 4 * hh_e);
.Lfox_pf_skip:
	s_or_b64 exec, exec, s[2:3]
	v_mov_b32_e32 v74, v190
	v_mov_b32_e32 v70, v161
	s_nop 1
	v_permlane32_swap_b32 v190, v74
	s_nop 1
	s_ashr_i32 s15, s14, 31
	s_lshl_b64 s[0:1], s[14:15], 13
	s_ashr_i32 s2, s13, 31
	s_add_u32 s0, s0, s13
	v_and_b32_e32 v0, 31, v70
	s_addc_u32 s1, s1, s2
	v_lshl_add_u64 v[66:67], s[0:1], 0, v[0:1]
	v_readlane_b32 s84, v255, 7
	v_ashrrev_i32_e32 v0, 3, v70
	v_lshlrev_b64 v[68:69], 14, v[66:67]
	v_readlane_b32 s85, v255, 8
	v_and_b32_e32 v70, -4, v0
	s_mov_b32 s13, s89
	v_lshl_add_u64 v[68:69], s[84:85], 0, v[68:69]
	v_ashrrev_i32_e32 v71, 31, v70
	v_lshl_add_u64 v[68:69], v[68:69], 0, s[12:13]
	v_lshlrev_b64 v[70:71], 1, v[70:71]
	v_lshl_add_u64 v[68:69], v[68:69], 0, v[70:71]
	s_movk_i32 s0, 0x3000
	v_add_co_u32_e32 v72, vcc, s0, v68
	s_mov_b64 s[0:1], 0x3000
	s_nop 0
	v_addc_co_u32_e32 v73, vcc, 0, v69, vcc
	global_load_dwordx2 v[90:91], v[72:73], off
	v_lshl_add_u64 v[68:69], v[68:69], 0, s[0:1]
	global_load_dwordx2 v[92:93], v[68:69], off offset:16
	global_load_dwordx2 v[94:95], v[68:69], off offset:32
	v_add_f32_e32 v0, v190, v74
	v_div_scale_f32 v100, s[0:1], v0, v0, 1.0
	v_rcp_f32_e32 v101, v100
	v_readlane_b32 s94, v255, 5
	v_lshlrev_b64 v[66:67], 12, v[66:67]
	v_readlane_b32 s95, v255, 6
	v_fma_f32 v72, -v100, v101, 1.0
	v_fmac_f32_e32 v101, v72, v101
	v_lshl_add_u64 v[66:67], s[94:95], 0, v[66:67]
	v_lshl_add_u64 v[66:67], v[66:67], 0, s[12:13]
	v_lshl_add_u64 v[66:67], v[66:67], 0, v[70:71]
	global_load_dwordx2 v[96:97], v[68:69], off offset:48
	global_load_dwordx2 v[98:99], v[68:69], off offset:64
	global_load_dwordx2 v[88:89], v[68:69], off offset:80
	global_load_dwordx2 v[86:87], v[68:69], off offset:96
	global_load_dwordx2 v[84:85], v[68:69], off offset:112
	global_load_dwordx2 v[82:83], v[68:69], off offset:128
	global_load_dwordx2 v[80:81], v[68:69], off offset:144
	global_load_dwordx2 v[78:79], v[68:69], off offset:160
	global_load_dwordx2 v[76:77], v[68:69], off offset:176
	global_load_dwordx2 v[74:75], v[68:69], off offset:192
	global_load_dwordx2 v[72:73], v[68:69], off offset:208
	global_load_dwordx2 v[70:71], v[68:69], off offset:224
	s_nop 0
	global_load_dwordx2 v[68:69], v[68:69], off offset:240
	v_div_scale_f32 v102, vcc, 1.0, v0, 1.0
	v_mul_f32_e32 v103, v102, v101
	v_fma_f32 v104, -v100, v103, v102
	v_fmac_f32_e32 v103, v104, v101
	v_fma_f32 v100, -v100, v103, v102
	v_div_fmas_f32 v100, v100, v101, v103
	v_div_fixup_f32 v0, v100, v0, 1.0
	v_pk_mul_f32 v[50:51], v[50:51], v[0:1] op_sel_hi:[1,0]
	v_pk_mul_f32 v[52:53], v[52:53], v[0:1] op_sel_hi:[1,0]
	v_pk_mul_f32 v[54:55], v[54:55], v[0:1] op_sel_hi:[1,0]
	v_pk_mul_f32 v[34:35], v[34:35], v[0:1] op_sel_hi:[1,0]
	v_pk_mul_f32 v[36:37], v[36:37], v[0:1] op_sel_hi:[1,0]
	v_pk_mul_f32 v[38:39], v[38:39], v[0:1] op_sel_hi:[1,0]
	v_pk_mul_f32 v[18:19], v[18:19], v[0:1] op_sel_hi:[1,0]
	v_pk_mul_f32 v[20:21], v[20:21], v[0:1] op_sel_hi:[1,0]
	v_pk_mul_f32 v[22:23], v[22:23], v[0:1] op_sel_hi:[1,0]
	v_pk_mul_f32 v[2:3], v[2:3], v[0:1] op_sel_hi:[1,0]
	v_pk_mul_f32 v[4:5], v[4:5], v[0:1] op_sel_hi:[1,0]
	v_pk_mul_f32 v[6:7], v[6:7], v[0:1] op_sel_hi:[1,0]
	v_readlane_b32 s0, v254, 47
	v_readlane_b32 s28, v255, 9
	v_readlane_b32 s92, v255, 4
	v_readlane_b32 s29, v255, 10
	s_waitcnt vmcnt(15)
	v_lshlrev_b32_e32 v100, 16, v90
	v_and_b32_e32 v101, 0xffff0000, v90
	v_lshlrev_b32_e32 v90, 16, v91
	v_and_b32_e32 v91, 0xffff0000, v91
	v_mul_f32_e32 v104, 0xbfb8aa3b, v100
	v_mul_f32_e32 v105, 0xbfb8aa3b, v101
	v_mul_f32_e32 v106, 0xbfb8aa3b, v90
	v_mul_f32_e32 v107, 0xbfb8aa3b, v91
	v_exp_f32_e32 v104, v104
	v_exp_f32_e32 v105, v105
	v_exp_f32_e32 v106, v106
	v_exp_f32_e32 v107, v107
	v_add_f32_e32 v104, 1.0, v104
	v_add_f32_e32 v105, 1.0, v105
	v_add_f32_e32 v106, 1.0, v106
	v_add_f32_e32 v107, 1.0, v107
	v_rcp_f32_e32 v104, v104
	v_rcp_f32_e32 v105, v105
	v_rcp_f32_e32 v106, v106
	v_rcp_f32_e32 v107, v107
	s_waitcnt vmcnt(14)
	v_lshlrev_b32_e32 v102, 16, v92
	v_and_b32_e32 v103, 0xffff0000, v92
	v_lshlrev_b32_e32 v92, 16, v93
	v_and_b32_e32 v93, 0xffff0000, v93
	v_mul_f32_e32 v108, 0xbfb8aa3b, v102
	v_mul_f32_e32 v109, 0xbfb8aa3b, v103
	v_pk_mul_f32 v[100:101], v[104:105], v[100:101]
	v_pk_mul_f32 v[90:91], v[106:107], v[90:91]
	v_mul_f32_e32 v110, 0xbfb8aa3b, v92
	v_mul_f32_e32 v111, 0xbfb8aa3b, v93
	v_exp_f32_e32 v108, v108
	v_exp_f32_e32 v109, v109
	v_pk_mul_f32 v[50:51], v[50:51], v[100:101]
	v_pk_mul_f32 v[52:53], v[52:53], v[90:91]
	v_exp_f32_e32 v110, v110
	v_cvt_pk_bf16_f32 v50, v50, v51
	v_cvt_pk_bf16_f32 v51, v52, v53
	v_exp_f32_e32 v53, v111
	v_add_f32_e32 v108, 1.0, v108
	v_add_f32_e32 v109, 1.0, v109
	v_rcp_f32_e32 v108, v108
	v_rcp_f32_e32 v109, v109
	v_add_f32_e32 v52, 1.0, v110
	v_add_f32_e32 v53, 1.0, v53
	v_rcp_f32_e32 v52, v52
	v_rcp_f32_e32 v53, v53
	global_store_dwordx2 v[66:67], v[50:51], off
	v_pk_mul_f32 v[50:51], v[108:109], v[102:103]
	v_pk_mul_f32 v[52:53], v[52:53], v[92:93]
	v_pk_mul_f32 v[50:51], v[54:55], v[50:51]
	v_pk_mul_f32 v[54:55], v[56:57], v[0:1] op_sel_hi:[1,0]
	v_cvt_pk_bf16_f32 v50, v50, v51
	v_pk_mul_f32 v[52:53], v[54:55], v[52:53]
	s_waitcnt vmcnt(14)
	v_lshlrev_b32_e32 v56, 16, v95
	v_cvt_pk_bf16_f32 v51, v52, v53
	global_store_dwordx2 v[66:67], v[50:51], off offset:16
	v_lshlrev_b32_e32 v50, 16, v94
	v_mul_f32_e32 v51, 0xbfb8aa3b, v50
	v_exp_f32_e32 v52, v51
	v_and_b32_e32 v51, 0xffff0000, v94
	v_mul_f32_e32 v53, 0xbfb8aa3b, v51
	v_exp_f32_e32 v53, v53
	v_and_b32_e32 v57, 0xffff0000, v95
	v_add_f32_e32 v52, 1.0, v52
	v_pk_mul_f32 v[54:55], v[58:59], v[0:1] op_sel_hi:[1,0]
	v_add_f32_e32 v53, 1.0, v53
	v_mul_f32_e32 v58, 0xbfb8aa3b, v56
	v_mul_f32_e32 v59, 0xbfb8aa3b, v57
	v_rcp_f32_e32 v52, v52
	v_rcp_f32_e32 v53, v53
	v_exp_f32_e32 v58, v58
	v_exp_f32_e32 v59, v59
	v_pk_mul_f32 v[50:51], v[52:53], v[50:51]
	v_add_f32_e32 v52, 1.0, v58
	v_add_f32_e32 v53, 1.0, v59
	v_rcp_f32_e32 v52, v52
	v_rcp_f32_e32 v53, v53
	v_pk_mul_f32 v[50:51], v[54:55], v[50:51]
	v_pk_mul_f32 v[54:55], v[60:61], v[0:1] op_sel_hi:[1,0]
	v_cvt_pk_bf16_f32 v50, v50, v51
	v_pk_mul_f32 v[52:53], v[52:53], v[56:57]
	s_waitcnt vmcnt(14)
; __device__ __forceinline__ unsigned pk2(float lo, float hi) { f32x2 v = {lo, hi}; bf16x2_t b = __builtin_convertvector(v, bf16x2_t); return __builtin_bit_cast(unsigned, b); }
; __device__ __forceinline__ float silu_f(float z) { return z * __builtin_amdgcn_rcpf(1.0f + __expf(-z)); }
; template <int MODE>
; __device__ __forceinline__ void attn_unit(LAS unsigned char* lds, const bf16_t* __restrict__ qkvz, bf16_t* __restrict__ A2, const int b, const int hd, const int qb, const AttnX& X, const int tid) {
;     ...
;             for (int i4 = 0; i4 < 4; ++i4) { const int dd = 32 * d + 8 * i4 + 4 * hh_e; const u32x2 z2 = zz[d * 4 + i4];
;                 u32x2 w;
;                 w.x = pk2(O[d][4 * i4 + 0] * inv * silu_f(bflo(z2.x)), O[d][4 * i4 + 1] * inv * silu_f(bfhi(z2.x)));
;                 w.y = pk2(O[d][4 * i4 + 2] * inv * silu_f(bflo(z2.y)), O[d][4 * i4 + 3] * inv * silu_f(bfhi(z2.y)));
;                 *(u32x2*)(A2 + trow * DM + hd * C::DV + dd) = w; }
	v_lshlrev_b32_e32 v56, 16, v97
	v_pk_mul_f32 v[52:53], v[54:55], v[52:53]
	v_and_b32_e32 v57, 0xffff0000, v97
	v_cvt_pk_bf16_f32 v51, v52, v53
	global_store_dwordx2 v[66:67], v[50:51], off offset:32
	v_lshlrev_b32_e32 v50, 16, v96
	v_mul_f32_e32 v51, 0xbfb8aa3b, v50
	v_exp_f32_e32 v52, v51
	v_and_b32_e32 v51, 0xffff0000, v96
	v_mul_f32_e32 v53, 0xbfb8aa3b, v51
	v_exp_f32_e32 v53, v53
	v_add_f32_e32 v52, 1.0, v52
	v_mul_f32_e32 v58, 0xbfb8aa3b, v56
	v_mul_f32_e32 v59, 0xbfb8aa3b, v57
	v_add_f32_e32 v53, 1.0, v53
	v_rcp_f32_e32 v52, v52
	v_rcp_f32_e32 v53, v53
	v_exp_f32_e32 v58, v58
	v_exp_f32_e32 v59, v59
	v_pk_mul_f32 v[54:55], v[62:63], v[0:1] op_sel_hi:[1,0]
	v_pk_mul_f32 v[50:51], v[52:53], v[50:51]
	v_add_f32_e32 v52, 1.0, v58
	v_add_f32_e32 v53, 1.0, v59
	v_rcp_f32_e32 v52, v52
	v_rcp_f32_e32 v53, v53
	v_pk_mul_f32 v[50:51], v[54:55], v[50:51]
	v_pk_mul_f32 v[54:55], v[64:65], v[0:1] op_sel_hi:[1,0]
	v_cvt_pk_bf16_f32 v50, v50, v51
	v_pk_mul_f32 v[52:53], v[52:53], v[56:57]
	s_nop 0
	v_pk_mul_f32 v[52:53], v[54:55], v[52:53]
	s_waitcnt vmcnt(14)
	v_lshlrev_b32_e32 v54, 16, v99
	v_cvt_pk_bf16_f32 v51, v52, v53
	global_store_dwordx2 v[66:67], v[50:51], off offset:48
	v_lshlrev_b32_e32 v50, 16, v98
	v_mul_f32_e32 v51, 0xbfb8aa3b, v50
	v_exp_f32_e32 v52, v51
	v_and_b32_e32 v51, 0xffff0000, v98
	v_mul_f32_e32 v53, 0xbfb8aa3b, v51
	v_exp_f32_e32 v53, v53
	v_and_b32_e32 v55, 0xffff0000, v99
	v_add_f32_e32 v52, 1.0, v52
	v_mul_f32_e32 v56, 0xbfb8aa3b, v54
	v_add_f32_e32 v53, 1.0, v53
	v_mul_f32_e32 v57, 0xbfb8aa3b, v55
	v_rcp_f32_e32 v52, v52
	v_rcp_f32_e32 v53, v53
	v_exp_f32_e32 v56, v56
	v_exp_f32_e32 v57, v57
	v_pk_mul_f32 v[50:51], v[52:53], v[50:51]
	v_add_f32_e32 v52, 1.0, v56
	v_add_f32_e32 v53, 1.0, v57
	v_rcp_f32_e32 v52, v52
	v_rcp_f32_e32 v53, v53
	v_pk_mul_f32 v[34:35], v[34:35], v[50:51]
	v_pk_mul_f32 v[50:51], v[52:53], v[54:55]
	s_nop 0
	v_pk_mul_f32 v[36:37], v[36:37], v[50:51]
	v_cvt_pk_bf16_f32 v34, v34, v35
	v_cvt_pk_bf16_f32 v35, v36, v37
	global_store_dwordx2 v[66:67], v[34:35], off offset:64
	s_waitcnt vmcnt(15)
	v_lshlrev_b32_e32 v34, 16, v88
	v_mul_f32_e32 v35, 0xbfb8aa3b, v34
	v_exp_f32_e32 v36, v35
	v_and_b32_e32 v35, 0xffff0000, v88
	v_mul_f32_e32 v37, 0xbfb8aa3b, v35
	v_exp_f32_e32 v37, v37
	v_lshlrev_b32_e32 v50, 16, v89
	v_and_b32_e32 v51, 0xffff0000, v89
	v_add_f32_e32 v36, 1.0, v36
	v_add_f32_e32 v37, 1.0, v37
	v_mul_f32_e32 v52, 0xbfb8aa3b, v50
	v_mul_f32_e32 v53, 0xbfb8aa3b, v51
	v_rcp_f32_e32 v36, v36
	v_rcp_f32_e32 v37, v37
	v_exp_f32_e32 v52, v52
	v_exp_f32_e32 v53, v53
	v_pk_mul_f32 v[34:35], v[36:37], v[34:35]
	v_add_f32_e32 v36, 1.0, v52
	v_add_f32_e32 v37, 1.0, v53
	v_rcp_f32_e32 v36, v36
	v_rcp_f32_e32 v37, v37
	v_pk_mul_f32 v[34:35], v[38:39], v[34:35]
	v_pk_mul_f32 v[38:39], v[40:41], v[0:1] op_sel_hi:[1,0]
	v_cvt_pk_bf16_f32 v34, v34, v35
	v_pk_mul_f32 v[36:37], v[36:37], v[50:51]
	s_waitcnt vmcnt(14)
	v_lshlrev_b32_e32 v40, 16, v87
	v_pk_mul_f32 v[36:37], v[38:39], v[36:37]
	v_and_b32_e32 v41, 0xffff0000, v87
	v_cvt_pk_bf16_f32 v35, v36, v37
	global_store_dwordx2 v[66:67], v[34:35], off offset:80
	v_lshlrev_b32_e32 v34, 16, v86
	v_mul_f32_e32 v35, 0xbfb8aa3b, v34
	v_exp_f32_e32 v36, v35
	v_and_b32_e32 v35, 0xffff0000, v86
	v_mul_f32_e32 v37, 0xbfb8aa3b, v35
	v_exp_f32_e32 v37, v37
	v_add_f32_e32 v36, 1.0, v36
	v_pk_mul_f32 v[38:39], v[42:43], v[0:1] op_sel_hi:[1,0]
	v_mul_f32_e32 v42, 0xbfb8aa3b, v40
	v_add_f32_e32 v37, 1.0, v37
	v_mul_f32_e32 v43, 0xbfb8aa3b, v41
	v_rcp_f32_e32 v36, v36
	v_rcp_f32_e32 v37, v37
	v_exp_f32_e32 v42, v42
	v_exp_f32_e32 v43, v43
	v_pk_mul_f32 v[34:35], v[36:37], v[34:35]
	v_add_f32_e32 v36, 1.0, v42
	v_add_f32_e32 v37, 1.0, v43
	v_rcp_f32_e32 v36, v36
	v_rcp_f32_e32 v37, v37
	v_pk_mul_f32 v[34:35], v[38:39], v[34:35]
	v_pk_mul_f32 v[38:39], v[44:45], v[0:1] op_sel_hi:[1,0]
	v_cvt_pk_bf16_f32 v34, v34, v35
	v_pk_mul_f32 v[36:37], v[36:37], v[40:41]
	s_waitcnt vmcnt(14)
	v_lshlrev_b32_e32 v40, 16, v85
	v_pk_mul_f32 v[36:37], v[38:39], v[36:37]
	v_and_b32_e32 v41, 0xffff0000, v85
	v_cvt_pk_bf16_f32 v35, v36, v37
	global_store_dwordx2 v[66:67], v[34:35], off offset:96
	v_lshlrev_b32_e32 v34, 16, v84
	v_mul_f32_e32 v35, 0xbfb8aa3b, v34
	v_exp_f32_e32 v36, v35
	v_and_b32_e32 v35, 0xffff0000, v84
	v_mul_f32_e32 v37, 0xbfb8aa3b, v35
	v_exp_f32_e32 v37, v37
	v_add_f32_e32 v36, 1.0, v36
	v_mul_f32_e32 v42, 0xbfb8aa3b, v40
	v_mul_f32_e32 v43, 0xbfb8aa3b, v41
	v_add_f32_e32 v37, 1.0, v37
	v_rcp_f32_e32 v36, v36
	v_rcp_f32_e32 v37, v37
	v_exp_f32_e32 v42, v42
	v_exp_f32_e32 v43, v43
	v_pk_mul_f32 v[38:39], v[46:47], v[0:1] op_sel_hi:[1,0]
	v_pk_mul_f32 v[34:35], v[36:37], v[34:35]
	v_add_f32_e32 v36, 1.0, v42
	v_add_f32_e32 v37, 1.0, v43
	v_rcp_f32_e32 v36, v36
	v_rcp_f32_e32 v37, v37
	v_pk_mul_f32 v[34:35], v[38:39], v[34:35]
	v_pk_mul_f32 v[38:39], v[48:49], v[0:1] op_sel_hi:[1,0]
	v_cvt_pk_bf16_f32 v34, v34, v35
	v_pk_mul_f32 v[36:37], v[36:37], v[40:41]
	s_nop 0
	v_pk_mul_f32 v[36:37], v[38:39], v[36:37]
	s_waitcnt vmcnt(14)
	v_lshlrev_b32_e32 v38, 16, v83
	v_cvt_pk_bf16_f32 v35, v36, v37
	global_store_dwordx2 v[66:67], v[34:35], off offset:112
	v_lshlrev_b32_e32 v34, 16, v82
	v_mul_f32_e32 v35, 0xbfb8aa3b, v34
	v_exp_f32_e32 v36, v35
	v_and_b32_e32 v35, 0xffff0000, v82
	v_mul_f32_e32 v37, 0xbfb8aa3b, v35
	v_exp_f32_e32 v37, v37
	v_and_b32_e32 v39, 0xffff0000, v83
	v_add_f32_e32 v36, 1.0, v36
	v_mul_f32_e32 v40, 0xbfb8aa3b, v38
	v_add_f32_e32 v37, 1.0, v37
	v_mul_f32_e32 v41, 0xbfb8aa3b, v39
	v_rcp_f32_e32 v36, v36
	v_rcp_f32_e32 v37, v37
	v_exp_f32_e32 v40, v40
	v_exp_f32_e32 v41, v41
	v_pk_mul_f32 v[34:35], v[36:37], v[34:35]
	v_add_f32_e32 v36, 1.0, v40
	v_add_f32_e32 v37, 1.0, v41
	v_rcp_f32_e32 v36, v36
	v_rcp_f32_e32 v37, v37
	v_pk_mul_f32 v[18:19], v[18:19], v[34:35]
	v_pk_mul_f32 v[34:35], v[36:37], v[38:39]
	s_nop 0
	v_pk_mul_f32 v[20:21], v[20:21], v[34:35]
	v_cvt_pk_bf16_f32 v18, v18, v19
	v_cvt_pk_bf16_f32 v19, v20, v21
	global_store_dwordx2 v[66:67], v[18:19], off offset:128
	s_waitcnt vmcnt(15)
; __device__ __forceinline__ unsigned pk2(float lo, float hi) { f32x2 v = {lo, hi}; bf16x2_t b = __builtin_convertvector(v, bf16x2_t); return __builtin_bit_cast(unsigned, b); }
; __device__ __forceinline__ float silu_f(float z) { return z * __builtin_amdgcn_rcpf(1.0f + __expf(-z)); }
; template <int MODE>
; __device__ __forceinline__ void attn_unit(LAS unsigned char* lds, const bf16_t* __restrict__ qkvz, bf16_t* __restrict__ A2, const int b, const int hd, const int qb, const AttnX& X, const int tid) {
;     ...
;             for (int i4 = 0; i4 < 4; ++i4) { const int dd = 32 * d + 8 * i4 + 4 * hh_e; const u32x2 z2 = zz[d * 4 + i4];
;                 u32x2 w;
;                 w.x = pk2(O[d][4 * i4 + 0] * inv * silu_f(bflo(z2.x)), O[d][4 * i4 + 1] * inv * silu_f(bfhi(z2.x)));
;                 w.y = pk2(O[d][4 * i4 + 2] * inv * silu_f(bflo(z2.y)), O[d][4 * i4 + 3] * inv * silu_f(bfhi(z2.y)));
;                 *(u32x2*)(A2 + trow * DM + hd * C::DV + dd) = w; }
; __device__ __forceinline__ void phase_attn_fox(const Params& p, LAS unsigned char* lds) {
;     ...
;     for (int u = bx; u < 2048; u += G) { const int j = u & 255, r = u >> 8, bh = j & 63, gg = j >> 6;
;         const int qb = 31 - ((r & 1) ? 4 * r + 3 - gg : 4 * r + gg);
;         attn_unit<2>(lds, QKVZ, A2, bh >> 4, bh & 15, qb, X, tid); }
	v_lshlrev_b32_e32 v18, 16, v80
	v_mul_f32_e32 v19, 0xbfb8aa3b, v18
	v_exp_f32_e32 v20, v19
	v_and_b32_e32 v19, 0xffff0000, v80
	v_mul_f32_e32 v21, 0xbfb8aa3b, v19
	v_exp_f32_e32 v21, v21
	v_lshlrev_b32_e32 v34, 16, v81
	v_and_b32_e32 v35, 0xffff0000, v81
	v_add_f32_e32 v20, 1.0, v20
	v_add_f32_e32 v21, 1.0, v21
	v_mul_f32_e32 v36, 0xbfb8aa3b, v34
	v_mul_f32_e32 v37, 0xbfb8aa3b, v35
	v_rcp_f32_e32 v20, v20
	v_rcp_f32_e32 v21, v21
	v_exp_f32_e32 v36, v36
	v_exp_f32_e32 v37, v37
	v_pk_mul_f32 v[18:19], v[20:21], v[18:19]
	v_add_f32_e32 v20, 1.0, v36
	v_add_f32_e32 v21, 1.0, v37
	v_rcp_f32_e32 v20, v20
	v_rcp_f32_e32 v21, v21
	v_pk_mul_f32 v[18:19], v[22:23], v[18:19]
	v_pk_mul_f32 v[22:23], v[24:25], v[0:1] op_sel_hi:[1,0]
	v_cvt_pk_bf16_f32 v18, v18, v19
	v_pk_mul_f32 v[20:21], v[20:21], v[34:35]
	s_waitcnt vmcnt(14)
	v_lshlrev_b32_e32 v24, 16, v79
	v_pk_mul_f32 v[20:21], v[22:23], v[20:21]
	v_and_b32_e32 v25, 0xffff0000, v79
	v_cvt_pk_bf16_f32 v19, v20, v21
	global_store_dwordx2 v[66:67], v[18:19], off offset:144
	v_lshlrev_b32_e32 v18, 16, v78
	v_mul_f32_e32 v19, 0xbfb8aa3b, v18
	v_exp_f32_e32 v20, v19
	v_and_b32_e32 v19, 0xffff0000, v78
	v_mul_f32_e32 v21, 0xbfb8aa3b, v19
	v_exp_f32_e32 v21, v21
	v_add_f32_e32 v20, 1.0, v20
	v_pk_mul_f32 v[22:23], v[26:27], v[0:1] op_sel_hi:[1,0]
	v_mul_f32_e32 v26, 0xbfb8aa3b, v24
	v_add_f32_e32 v21, 1.0, v21
	v_mul_f32_e32 v27, 0xbfb8aa3b, v25
	v_rcp_f32_e32 v20, v20
	v_rcp_f32_e32 v21, v21
	v_exp_f32_e32 v26, v26
	v_exp_f32_e32 v27, v27
	v_pk_mul_f32 v[18:19], v[20:21], v[18:19]
	v_add_f32_e32 v20, 1.0, v26
	v_add_f32_e32 v21, 1.0, v27
	v_rcp_f32_e32 v20, v20
	v_rcp_f32_e32 v21, v21
	v_pk_mul_f32 v[18:19], v[22:23], v[18:19]
	v_pk_mul_f32 v[22:23], v[28:29], v[0:1] op_sel_hi:[1,0]
	v_cvt_pk_bf16_f32 v18, v18, v19
	v_pk_mul_f32 v[20:21], v[20:21], v[24:25]
	s_waitcnt vmcnt(14)
	v_lshlrev_b32_e32 v24, 16, v77
	v_pk_mul_f32 v[20:21], v[22:23], v[20:21]
	v_and_b32_e32 v25, 0xffff0000, v77
	v_cvt_pk_bf16_f32 v19, v20, v21
	global_store_dwordx2 v[66:67], v[18:19], off offset:160
	v_lshlrev_b32_e32 v18, 16, v76
	v_mul_f32_e32 v19, 0xbfb8aa3b, v18
	v_exp_f32_e32 v20, v19
	v_and_b32_e32 v19, 0xffff0000, v76
	v_mul_f32_e32 v21, 0xbfb8aa3b, v19
	v_exp_f32_e32 v21, v21
	v_add_f32_e32 v20, 1.0, v20
	v_mul_f32_e32 v26, 0xbfb8aa3b, v24
	v_mul_f32_e32 v27, 0xbfb8aa3b, v25
	v_add_f32_e32 v21, 1.0, v21
	v_rcp_f32_e32 v20, v20
	v_rcp_f32_e32 v21, v21
	v_exp_f32_e32 v26, v26
	v_exp_f32_e32 v27, v27
	v_pk_mul_f32 v[22:23], v[30:31], v[0:1] op_sel_hi:[1,0]
	v_pk_mul_f32 v[18:19], v[20:21], v[18:19]
	v_add_f32_e32 v20, 1.0, v26
	v_add_f32_e32 v21, 1.0, v27
	v_rcp_f32_e32 v20, v20
	v_rcp_f32_e32 v21, v21
	v_pk_mul_f32 v[18:19], v[22:23], v[18:19]
	v_pk_mul_f32 v[22:23], v[32:33], v[0:1] op_sel_hi:[1,0]
	v_cvt_pk_bf16_f32 v18, v18, v19
	v_pk_mul_f32 v[20:21], v[20:21], v[24:25]
	s_nop 0
	v_pk_mul_f32 v[20:21], v[22:23], v[20:21]
	s_waitcnt vmcnt(14)
	v_lshlrev_b32_e32 v22, 16, v75
	v_cvt_pk_bf16_f32 v19, v20, v21
	global_store_dwordx2 v[66:67], v[18:19], off offset:176
	v_lshlrev_b32_e32 v18, 16, v74
	v_mul_f32_e32 v19, 0xbfb8aa3b, v18
	v_exp_f32_e32 v20, v19
	v_and_b32_e32 v19, 0xffff0000, v74
	v_mul_f32_e32 v21, 0xbfb8aa3b, v19
	v_exp_f32_e32 v21, v21
	v_and_b32_e32 v23, 0xffff0000, v75
	v_add_f32_e32 v20, 1.0, v20
	v_mul_f32_e32 v24, 0xbfb8aa3b, v22
	v_add_f32_e32 v21, 1.0, v21
	v_mul_f32_e32 v25, 0xbfb8aa3b, v23
	v_rcp_f32_e32 v20, v20
	v_rcp_f32_e32 v21, v21
	v_exp_f32_e32 v24, v24
	v_exp_f32_e32 v25, v25
	v_pk_mul_f32 v[18:19], v[20:21], v[18:19]
	v_add_f32_e32 v20, 1.0, v24
	v_add_f32_e32 v21, 1.0, v25
	v_rcp_f32_e32 v20, v20
	v_rcp_f32_e32 v21, v21
	v_pk_mul_f32 v[2:3], v[2:3], v[18:19]
	v_pk_mul_f32 v[18:19], v[20:21], v[22:23]
	s_nop 0
	v_pk_mul_f32 v[4:5], v[4:5], v[18:19]
	v_cvt_pk_bf16_f32 v2, v2, v3
	v_cvt_pk_bf16_f32 v3, v4, v5
	global_store_dwordx2 v[66:67], v[2:3], off offset:192
	s_waitcnt vmcnt(15)
	v_lshlrev_b32_e32 v2, 16, v72
	v_mul_f32_e32 v3, 0xbfb8aa3b, v2
	v_exp_f32_e32 v4, v3
	v_and_b32_e32 v3, 0xffff0000, v72
	v_mul_f32_e32 v5, 0xbfb8aa3b, v3
	v_exp_f32_e32 v5, v5
	v_lshlrev_b32_e32 v18, 16, v73
	v_and_b32_e32 v19, 0xffff0000, v73
	v_add_f32_e32 v4, 1.0, v4
	v_add_f32_e32 v5, 1.0, v5
	v_mul_f32_e32 v20, 0xbfb8aa3b, v18
	v_mul_f32_e32 v21, 0xbfb8aa3b, v19
	v_rcp_f32_e32 v4, v4
	v_rcp_f32_e32 v5, v5
	v_exp_f32_e32 v20, v20
	v_exp_f32_e32 v21, v21
	v_pk_mul_f32 v[2:3], v[4:5], v[2:3]
	v_add_f32_e32 v4, 1.0, v20
	v_add_f32_e32 v5, 1.0, v21
	v_rcp_f32_e32 v4, v4
	v_rcp_f32_e32 v5, v5
	v_pk_mul_f32 v[2:3], v[6:7], v[2:3]
	v_pk_mul_f32 v[6:7], v[8:9], v[0:1] op_sel_hi:[1,0]
	v_cvt_pk_bf16_f32 v2, v2, v3
	v_pk_mul_f32 v[4:5], v[4:5], v[18:19]
	s_waitcnt vmcnt(14)
	v_lshlrev_b32_e32 v8, 16, v71
	v_pk_mul_f32 v[4:5], v[6:7], v[4:5]
	v_and_b32_e32 v9, 0xffff0000, v71
	v_cvt_pk_bf16_f32 v3, v4, v5
	global_store_dwordx2 v[66:67], v[2:3], off offset:208
	v_lshlrev_b32_e32 v2, 16, v70
	v_mul_f32_e32 v3, 0xbfb8aa3b, v2
	v_exp_f32_e32 v4, v3
	v_and_b32_e32 v3, 0xffff0000, v70
	v_mul_f32_e32 v5, 0xbfb8aa3b, v3
	v_exp_f32_e32 v5, v5
	v_add_f32_e32 v4, 1.0, v4
	v_pk_mul_f32 v[6:7], v[10:11], v[0:1] op_sel_hi:[1,0]
	v_mul_f32_e32 v10, 0xbfb8aa3b, v8
	v_add_f32_e32 v5, 1.0, v5
	v_mul_f32_e32 v11, 0xbfb8aa3b, v9
	v_rcp_f32_e32 v4, v4
	v_rcp_f32_e32 v5, v5
	v_exp_f32_e32 v10, v10
	v_exp_f32_e32 v11, v11
	v_pk_mul_f32 v[2:3], v[4:5], v[2:3]
	v_add_f32_e32 v4, 1.0, v10
	v_add_f32_e32 v5, 1.0, v11
	v_rcp_f32_e32 v4, v4
	v_rcp_f32_e32 v5, v5
	v_pk_mul_f32 v[2:3], v[6:7], v[2:3]
	v_pk_mul_f32 v[6:7], v[12:13], v[0:1] op_sel_hi:[1,0]
	v_cvt_pk_bf16_f32 v2, v2, v3
	v_pk_mul_f32 v[4:5], v[4:5], v[8:9]
	s_waitcnt vmcnt(14)
	v_lshlrev_b32_e32 v8, 16, v69
	v_pk_mul_f32 v[4:5], v[6:7], v[4:5]
	v_and_b32_e32 v9, 0xffff0000, v69
	v_cvt_pk_bf16_f32 v3, v4, v5
	global_store_dwordx2 v[66:67], v[2:3], off offset:224
	v_lshlrev_b32_e32 v2, 16, v68
	v_mul_f32_e32 v3, 0xbfb8aa3b, v2
	v_exp_f32_e32 v4, v3
	v_and_b32_e32 v3, 0xffff0000, v68
	v_mul_f32_e32 v5, 0xbfb8aa3b, v3
	v_exp_f32_e32 v5, v5
	v_add_f32_e32 v4, 1.0, v4
	v_mul_f32_e32 v10, 0xbfb8aa3b, v8
	v_mul_f32_e32 v11, 0xbfb8aa3b, v9
	v_add_f32_e32 v5, 1.0, v5
	v_rcp_f32_e32 v4, v4
	v_rcp_f32_e32 v5, v5
	v_exp_f32_e32 v10, v10
	v_exp_f32_e32 v11, v11
	v_pk_mul_f32 v[6:7], v[14:15], v[0:1] op_sel_hi:[1,0]
	v_pk_mul_f32 v[2:3], v[4:5], v[2:3]
	v_add_f32_e32 v4, 1.0, v10
	v_add_f32_e32 v5, 1.0, v11
	v_rcp_f32_e32 v4, v4
	v_rcp_f32_e32 v5, v5
	v_pk_mul_f32 v[2:3], v[6:7], v[2:3]
	v_pk_mul_f32 v[6:7], v[16:17], v[0:1] op_sel_hi:[1,0]
	v_cvt_pk_bf16_f32 v2, v2, v3
	v_pk_mul_f32 v[4:5], v[4:5], v[8:9]
	s_nop 0
	v_pk_mul_f32 v[4:5], v[6:7], v[4:5]
	s_nop 0
	v_cvt_pk_bf16_f32 v3, v4, v5
	global_store_dwordx2 v[66:67], v[2:3], off offset:240
	v_cmp_eq_u32_e64 s[0:1], 0, v212
	s_and_saveexec_b64 s[2:3], s[0:1]
	s_cbranch_execz .Lfox_nofetch
	s_waitcnt vmcnt(16)
	v_mov_b32_e32 v251, 0x23ff8
	ds_write_b32 v251, v250
